# adds counted vmcnt(16) at the w_in and gate unit heads instead of vmcnt(0)
# speedup vs baseline: 1.0052x; 1.0015x over previous
; __device__ __forceinline__ const char* a_tile(const Gemm& g, const Unit& u) { return (const char*)(g.A + ((long)u.z1 * g.aS1 + (long)u.z2 * g.aS2 + (long)u.pm * BM * g.lda)); }
; __device__ __forceinline__ const char* b_tile(const Gemm& g, const Unit& u) { return (const char*)(g.Bt + ((long)u.z1 * g.bS1 + (long)u.z2 * g.bS2 + (long)u.pn * BM * g.ldb)); }
; template <class Epi>
; __device__ __forceinline__ void gemm_phase(PG8_LAS unsigned char* lds, PG8_LAS unsigned char* xl, const Gemm g, const Sched& S, const Epi& E, const int wid) {
;     ...
;     for (;;) {
;         const bool has_next = S.next(ui + 1, nxt);
;         const char* nA = has_next ? a_tile(g, nxt) : cA; const char* nB = has_next ? b_tile(g, nxt) : cB;
;     ...
;           if constexpr (Epi::PRE) {
; #pragma unroll
;               for (int k = 0; k < 8; ++k) prc[k] = prn[k]; } }
.LBB0_234:
	s_andn2_b64 vcc, exec, s[8:9]
	s_mov_b32 s12, s56
	s_mov_b32 s48, s58
	s_mov_b64 s[30:31], s[52:53]
	s_mov_b64 s[20:21], s[36:37]
	s_waitcnt vmcnt(16)
	v_mov_b64_e32 v[152:153], v[24:25]
	v_mov_b64_e32 v[16:17], v[22:23]
	v_mov_b64_e32 v[154:155], v[20:21]
	v_mov_b64_e32 v[90:91], v[18:19]
	s_cbranch_vccz .LBB0_334

; __device__ __forceinline__ const char* a_tile(const Gemm& g, const Unit& u) { return (const char*)(g.A + ((long)u.z1 * g.aS1 + (long)u.z2 * g.aS2 + (long)u.pm * BM * g.lda)); }
; __device__ __forceinline__ const char* b_tile(const Gemm& g, const Unit& u) { return (const char*)(g.Bt + ((long)u.z1 * g.bS1 + (long)u.z2 * g.bS2 + (long)u.pn * BM * g.ldb)); }
; template <class Epi>
; __device__ __forceinline__ void gemm_phase(PG8_LAS unsigned char* lds, PG8_LAS unsigned char* xl, const Gemm g, const Sched& S, const Epi& E, const int wid) {
;     ...
;     for (;;) {
;         const bool has_next = S.next(ui + 1, nxt);
;         const char* nA = has_next ? a_tile(g, nxt) : cA; const char* nB = has_next ? b_tile(g, nxt) : cB;
;     ...
;           if constexpr (Epi::PRE) {
; #pragma unroll
;               for (int k = 0; k < 8; ++k) prc[k] = prn[k]; } }
.LBB0_523:
	s_andn2_b64 vcc, exec, s[8:9]
	s_mov_b32 s44, s58
	s_mov_b32 s40, s36
	s_mov_b64 s[20:21], s[30:31]
	s_mov_b64 s[12:13], s[42:43]
	s_waitcnt vmcnt(16)
	v_mov_b64_e32 v[152:153], v[28:29]
	v_mov_b64_e32 v[16:17], v[26:27]
	v_mov_b64_e32 v[154:155], v[24:25]
	v_mov_b64_e32 v[90:91], v[22:23]
	s_cbranch_vccz .LBB0_623
